# mLSTM phases B/C3/E: LDS fragment reads hoisted behind counted lgkmcnt waits; RWKV prep: 36 redundant LoRA A-fragment re-reads removed
# speedup vs baseline: 1.0233x; 1.0027x over previous
; __device__ __forceinline__ void rwkv_block(KP p, int o, int b, int hd, LAS unsigned char* lds, const bf16_t* P, bf16_t* YB) {
;     ...
;         auto load_rows = [&](int m, Raw& d) {
;             const int sidx = m * 16 + 4 * q + t4;
;             const bf16_t* row = P + (rbase + sidx) * NPROJ;
;             d.r[1] = *(const u32x2*)(row + ch0); d.k[1] = *(const u32x2*)(row + 512 + ch0); d.v[1] = *(const u32x2*)(row + 1024 + ch0); d.l[1] = *(const u32x4*)(row + 1536 + 8 * jg);
;             if (sidx > 0) { const bf16_t* pr = row - NPROJ; d.r[0] = *(const u32x2*)(pr + ch0); d.k[0] = *(const u32x2*)(pr + 512 + ch0); d.v[0] = *(const u32x2*)(pr + 1024 + ch0); d.l[0] = *(const u32x4*)(pr + 1536 + 8 * jg); }
;             else { d.r[0] = (u32x2){0u, 0u}; d.k[0] = (u32x2){0u, 0u}; d.v[0] = (u32x2){0u, 0u}; d.l[0] = (u32x4){0u, 0u, 0u, 0u}; }
;         };
;         auto unpack4 = [](u32x2 w) { return (f32x4){__uint_as_float(w.x << 16), __uint_as_float(w.x & 0xFFFF0000u), __uint_as_float(w.y << 16), __uint_as_float(w.y & 0xFFFF0000u)}; };
;         auto red16 = [](float v) { v += dpp_f<0xB1>(v); v += dpp_f<0x4E>(v); v += dpp_f<0x141>(v); v += dpp_f<0x140>(v); return v; };
;         auto prep = [&](int m, const Raw& d) {
;             LAS float* B = (LAS float*)(lds + BUF0 + (m & 1) * BUFSZ);
;             LAS float* Wd = B; LAS float* KK = B + 1024; LAS float* BB = B + 2048; LAS float* KM = B + 3072; LAS float* Rr = B + 4096; LAS float* Vv = B + 5120; LAS float* Gg = B + 6144; LAS float* Bon = B + 8192;
;             const int tt = 4 * q + t4;
;             f32x4 cv, pv;
;             cv = unpack4(d.r[1]); pv = unpack4(d.r[0]); const f32x4 rr = cv + mu_r * (pv - cv);
;             cv = unpack4(d.k[1]); pv = unpack4(d.k[0]); const f32x4 k0 = cv + mu_k * (pv - cv);
;             cv = unpack4(d.v[1]); pv = unpack4(d.v[0]); const f32x4 vv = cv + mu_v * (pv - cv);
;             {
;                 f32x4 la, lb;
;                 cv = unpack4((u32x2){d.l[1].x, d.l[1].y}); pv = unpack4((u32x2){d.l[0].x, d.l[0].y}); la = cv + mu_la * (pv - cv);
;                 cv = unpack4((u32x2){d.l[1].z, d.l[1].w}); pv = unpack4((u32x2){d.l[0].z, d.l[0].w}); lb = cv + mu_lb * (pv - cv);
;                 float o8[8];
; #pragma unroll
;                 for (int i = 0; i < 4; ++i) {
;                     const float sa = sigmoidf_(lsc * la[i]), sb = sigmoidf_(lsc * lb[i]);
.LBB0_191:
	s_or_b64 exec, exec, s[10:11]
	s_movk_i32 s1, 0x1100
	v_mul_lo_u32 v0, v92, s1
	v_add_u32_e32 v94, 0, v0
	v_add3_u32 v0, v64, v131, 16
	v_lshl_add_u64 v[2:3], s[22:23], 0, v[0:1]
	v_mov_b64_e32 v[60:61], s[94:95]
	v_mad_u64_u32 v[60:61], s[12:13], v2, s81, v[60:61]
	v_lshlrev_b32_e32 v65, 3, v142
	v_mad_i32_i24 v61, v3, s81, v61
	v_lshl_add_u64 v[62:63], v[60:61], 0, v[96:97]
	v_lshlrev_b32_e32 v2, 1, v65
	v_mov_b32_e32 v3, v1
	s_movk_i32 s1, 0xf000
	v_lshl_add_u64 v[64:65], v[60:61], 0, v[2:3]
	v_add_co_u32_e32 v60, vcc, s1, v62
	global_load_dwordx2 v[120:121], v[62:63], off
	global_load_dwordx2 v[118:119], v[62:63], off offset:1024
	global_load_dwordx2 v[116:117], v[62:63], off offset:2048
	v_addc_co_u32_e32 v61, vcc, -1, v63, vcc
	global_load_dwordx2 v[122:123], v[60:61], off offset:-2560
	global_load_dwordx2 v[124:125], v[60:61], off offset:-1536
	global_load_dwordx2 v[126:127], v[60:61], off offset:-512
	s_nop 0
	global_load_dwordx4 v[60:63], v[64:65], off offset:3072
	s_nop 0
	global_load_dwordx4 v[64:67], v[64:65], off offset:-3584
	s_waitcnt vmcnt(8)
	v_lshlrev_b32_e32 v0, 16, v52
	v_lshlrev_b32_e32 v70, 16, v56
	v_lshlrev_b32_e32 v74, 16, v54
	v_lshlrev_b32_e32 v78, 16, v58
	v_cmp_gt_u32_e64 s[10:11], 4, v142
	v_sub_f32_e32 v70, v70, v0
	v_sub_f32_e32 v78, v78, v74
	v_cndmask_b32_e64 v103, 1.0, 2.0, s[10:11]
	v_fmac_f32_e32 v0, v16, v70
	v_fmac_f32_e32 v74, v28, v78
	v_mul_f32_e32 v70, v103, v0
	v_mul_f32_e32 v78, v103, v74
	v_mul_f32_e32 v70, 0xbfb8aa3b, v70
	v_mul_f32_e32 v78, 0xbfb8aa3b, v78
	v_exp_f32_e32 v70, v70
	v_exp_f32_e32 v78, v78
	v_and_b32_e32 v3, 0xffff0000, v52
	v_and_b32_e32 v71, 0xffff0000, v56
	v_add_f32_e32 v70, 1.0, v70
	v_add_f32_e32 v78, 1.0, v78
	v_rcp_f32_e32 v70, v70
	v_rcp_f32_e32 v78, v78
	v_and_b32_e32 v75, 0xffff0000, v54
	v_and_b32_e32 v79, 0xffff0000, v58
	v_sub_f32_e32 v71, v71, v3
	v_sub_f32_e32 v79, v79, v75
	v_cmp_gt_u32_e64 s[12:13], 8, v142
	v_fmac_f32_e32 v3, v17, v71
	v_fmac_f32_e32 v75, v29, v79
	v_fma_f32 v82, v70, 2.0, -1.0
	v_cndmask_b32_e64 v0, v70, v0, s[12:13]
	v_fma_f32 v70, v78, 2.0, -1.0
	v_cndmask_b32_e64 v74, v78, v74, s[12:13]
	v_mul_f32_e32 v71, v103, v3
	v_mul_f32_e32 v78, v103, v75
	v_mul_f32_e32 v71, 0xbfb8aa3b, v71
	v_mul_f32_e32 v78, 0xbfb8aa3b, v78
	v_exp_f32_e32 v71, v71
	v_exp_f32_e32 v78, v78
	v_lshlrev_b32_e32 v68, 16, v53
	v_lshlrev_b32_e32 v72, 16, v57
	v_sub_f32_e32 v72, v72, v68
	v_fmac_f32_e32 v68, v18, v72
	v_add_f32_e32 v71, 1.0, v71
	v_cndmask_b32_e64 v70, v74, v70, s[10:11]
	v_add_f32_e32 v74, 1.0, v78
	v_mul_f32_e32 v72, v103, v68
	v_rcp_f32_e32 v71, v71
	v_rcp_f32_e32 v74, v74
	v_mul_f32_e32 v72, 0xbfb8aa3b, v72
	v_lshlrev_b32_e32 v76, 16, v55
	v_lshlrev_b32_e32 v80, 16, v59
	v_exp_f32_e32 v72, v72
	v_sub_f32_e32 v80, v80, v76
	v_fmac_f32_e32 v76, v30, v80
	v_fma_f32 v78, v71, 2.0, -1.0
	v_cndmask_b32_e64 v3, v71, v3, s[12:13]
	v_fma_f32 v71, v74, 2.0, -1.0
	v_cndmask_b32_e64 v74, v74, v75, s[12:13]
	v_mul_f32_e32 v75, v103, v76
	v_mul_f32_e32 v75, 0xbfb8aa3b, v75
	v_add_f32_e32 v72, 1.0, v72
	v_exp_f32_e32 v75, v75
	v_rcp_f32_e32 v72, v72
	v_and_b32_e32 v69, 0xffff0000, v53
	v_and_b32_e32 v73, 0xffff0000, v57
	v_and_b32_e32 v77, 0xffff0000, v55
	v_and_b32_e32 v81, 0xffff0000, v59
	v_sub_f32_e32 v73, v73, v69
	v_sub_f32_e32 v81, v81, v77
	v_cndmask_b32_e64 v71, v74, v71, s[10:11]
	v_add_f32_e32 v74, 1.0, v75
	v_fma_f32 v75, v72, 2.0, -1.0
	v_cndmask_b32_e64 v68, v72, v68, s[12:13]
	v_fmac_f32_e32 v69, v19, v73
	v_fmac_f32_e32 v77, v31, v81
	v_cndmask_b32_e64 v72, v68, v75, s[10:11]
	v_mul_f32_e32 v73, v103, v69
	v_mul_f32_e32 v75, v103, v77
	v_rcp_f32_e32 v74, v74
	v_mul_f32_e32 v73, 0xbfb8aa3b, v73
	v_mul_f32_e32 v75, 0xbfb8aa3b, v75
	v_exp_f32_e32 v73, v73
	v_exp_f32_e32 v75, v75
	v_fma_f32 v68, v74, 2.0, -1.0
	v_cndmask_b32_e64 v74, v74, v76, s[12:13]
	v_add_f32_e32 v73, 1.0, v73
	v_cndmask_b32_e64 v74, v74, v68, s[10:11]
	v_add_f32_e32 v68, 1.0, v75
	v_rcp_f32_e32 v73, v73
	v_rcp_f32_e32 v68, v68
	v_cndmask_b32_e64 v0, v0, v82, s[10:11]
	v_cndmask_b32_e64 v3, v3, v78, s[10:11]
	v_fma_f32 v75, v73, 2.0, -1.0
	v_cndmask_b32_e64 v69, v73, v69, s[12:13]
	v_fma_f32 v73, v68, 2.0, -1.0
	v_cndmask_b32_e64 v68, v68, v77, s[12:13]
	s_movk_i32 s1, 0x110
	v_cndmask_b32_e64 v69, v69, v75, s[10:11]
	v_cndmask_b32_e64 v73, v68, v73, s[10:11]
	v_cvt_pk_bf16_f32 v68, v0, v3
	v_mad_u32_u24 v0, v131, s1, v94
	v_cvt_pk_bf16_f32 v69, v72, v69
	v_cvt_pk_bf16_f32 v70, v70, v71
	v_cvt_pk_bf16_f32 v71, v74, v73
	v_add_u32_e32 v132, v0, v102
	ds_write_b128 v132, v[68:71] offset:19456
	s_waitcnt lgkmcnt(0)
	v_mul_u32_u24_e32 v0, 0x110, v142
	v_lshlrev_b32_e32 v3, 4, v131
	v_add3_u32 v133, v94, v0, v3
	ds_read_b128 v[76:79], v133 offset:19584
	v_add_u32_e32 v0, 0, v3
	s_movk_i32 s1, 0x90
	v_mad_u32_u24 v3, v142, s1, v0
	ds_read_b128 v[80:83], v133 offset:19648
	ds_read_b128 v[68:71], v3 offset:10240
	ds_read_b128 v[84:87], v3 offset:10304
	s_waitcnt lgkmcnt(1)
	v_mfma_f32_16x16x32_bf16 v[88:91], v[76:79], v[68:71], 0
	ds_read_b128 v[72:75], v133 offset:19456
	ds_read_b128 v[68:71], v133 offset:19520
	s_movk_i32 s1, 0x50
	v_mad_u32_u24 v3, v142, s1, v0
	s_waitcnt lgkmcnt(2)
	v_mfma_f32_16x16x32_bf16 v[84:87], v[80:83], v[84:87], v[88:91]
	s_nop 2
	ds_read_b128 v[88:91], v3
	ds_read_b128 v[134:137], v3 offset:5120
	s_movk_i32 s1, 0xfbc0
	v_mad_u64_u32 v[128:129], s[14:15], v92, s1, v[94:95]
	s_waitcnt lgkmcnt(1)
	v_mfma_f32_16x16x32_bf16 v[88:91], v[72:75], v[88:91], 0
	v_lshl_add_u32 v3, v142, 2, v128
	v_cmp_eq_u32_e64 s[14:15], 0, v131
	s_waitcnt lgkmcnt(0)
	v_mfma_f32_16x16x32_bf16 v[92:95], v[68:71], v[134:137], 0
	v_add_u32_e32 v134, 0x9000, v3
	v_add_u32_e32 v135, 0x9400, v3
	v_add_u32_e32 v136, 0x9800, v3
	s_and_saveexec_b64 s[16:17], s[14:15]
	s_cbranch_execz .LBB0_193
	ds_write2_b32 v134, v88, v89 offset1:68
	s_nop 1
	ds_write2_b32 v135, v92, v93 offset0:16 offset1:84
	ds_write2_b32 v136, v84, v85 offset0:32 offset1:100
	ds_write2_b32 v134, v90, v91 offset0:136 offset1:204
	ds_write2_b32 v135, v94, v95 offset0:152 offset1:220
	ds_write2_b32 v136, v86, v87 offset0:168 offset1:236
; #define LAS __attribute__((address_space(3)))
; __device__ __forceinline__ f32x4 mfma16(bf16x8 a, bf16x8 b, f32x4 c) { return __builtin_amdgcn_mfma_f32_16x16x32_bf16(a, b, c, 0, 0, 0); }
; __device__ __forceinline__ void rwkv_block(KP p, int o, int b, int hd, LAS unsigned char* lds, const bf16_t* P, bf16_t* YB) {
;     ...
;             for (int ct = 0; ct < 4; ++ct) {
;                 f32x4 c0 = {0.f, 0.f, 0.f, 0.f}, c1 = {0.f, 0.f, 0.f, 0.f}, c2 = {0.f, 0.f, 0.f, 0.f};
;                 c0 = mfma16(*(const LAS bf16x8*)(Lin + fr * 136 + fq * 8), *(const LAS bf16x8*)(wBt + (ct * 16 + fr) * 40 + fq * 8), c0);
;                 c1 = mfma16(*(const LAS bf16x8*)(Lin + fr * 136 + 32 + fq * 8), *(const LAS bf16x8*)(aBt + (ct * 16 + fr) * 40 + fq * 8), c1);
; #pragma unroll
;                 for (int kb = 0; kb < 2; ++kb)
;                     c2 = mfma16(*(const LAS bf16x8*)(Lin + fr * 136 + 64 + kb * 32 + fq * 8), *(const LAS bf16x8*)(gBt + (ct * 16 + fr) * 72 + kb * 32 + fq * 8), c2);
;                 if (fq == 0) {
; #pragma unroll
;                     for (int jj = 0; jj < 4; ++jj) { Lout[jj * 68 + ct * 16 + fr] = c0[jj]; Lout[272 + jj * 68 + ct * 16 + fr] = c1[jj]; Lout[544 + jj * 68 + ct * 16 + fr] = c2[jj]; }
;                 }
;             }
.LBB0_193:
	s_or_b64 exec, exec, s[16:17]
	v_or_b32_e32 v97, 16, v142
	s_movk_i32 s1, 0x90
	v_mad_u32_u24 v92, v97, s1, v0
	ds_read_b128 v[84:87], v92 offset:10240
	s_movk_i32 s1, 0x50
	v_mad_u32_u24 v129, v97, s1, v0
	s_waitcnt lgkmcnt(0)
	v_mfma_f32_16x16x32_bf16 v[88:91], v[76:79], v[84:87], 0
	ds_read_b128 v[84:87], v129
	ds_read_b128 v[92:95], v92 offset:10304
	s_waitcnt lgkmcnt(0)
	v_mfma_f32_16x16x32_bf16 v[88:91], v[80:83], v[92:95], v[88:91]
	ds_read_b128 v[92:95], v129 offset:5120
	v_mfma_f32_16x16x32_bf16 v[84:87], v[72:75], v[84:87], 0
	s_waitcnt lgkmcnt(0)
	v_mfma_f32_16x16x32_bf16 v[92:95], v[68:71], v[92:95], 0
	s_and_saveexec_b64 s[16:17], s[14:15]
	s_cbranch_execz .LBB0_195
	s_nop 3
	ds_write2_b32 v134, v84, v85 offset0:16 offset1:84
	s_nop 0
	ds_write2_b32 v135, v92, v93 offset0:32 offset1:100
	ds_write2_b32 v136, v88, v89 offset0:48 offset1:116
	ds_write2_b32 v134, v86, v87 offset0:152 offset1:220
	ds_write2_b32 v135, v94, v95 offset0:168 offset1:236
	ds_write2_b32 v136, v90, v91 offset0:184 offset1:252
.LBB0_195:
	s_or_b64 exec, exec, s[16:17]
	s_nop 2
	v_mul_u32_u24_e32 v84, 0x90, v97
	v_add_u32_e32 v137, v84, v0
	ds_read_b128 v[84:87], v137 offset:12544
	ds_read_b128 v[92:95], v137 offset:12608
	v_mul_u32_u24_e32 v88, 0x50, v97
	v_add_u32_e32 v138, v88, v0
	v_add_u32_e32 v139, 0x9a00, v3
	s_waitcnt lgkmcnt(1)
	v_mfma_f32_16x16x32_bf16 v[88:91], v[76:79], v[84:87], 0
	ds_read_b128 v[84:87], v138 offset:1280
	s_waitcnt lgkmcnt(1)
	v_mfma_f32_16x16x32_bf16 v[88:91], v[80:83], v[92:95], v[88:91]
	ds_read_b128 v[92:95], v138 offset:6400
	s_waitcnt lgkmcnt(1)
	v_mfma_f32_16x16x32_bf16 v[84:87], v[72:75], v[84:87], 0
	s_waitcnt lgkmcnt(0)
	v_mfma_f32_16x16x32_bf16 v[92:95], v[68:71], v[92:95], 0
	s_and_saveexec_b64 s[16:17], s[14:15]
	s_cbranch_execz .LBB0_197
	s_nop 3
	ds_write2_b32 v134, v84, v85 offset0:32 offset1:100
	s_nop 0
	ds_write2_b32 v135, v92, v93 offset0:48 offset1:116
	ds_write2_b32 v136, v88, v89 offset0:64 offset1:132
	ds_write2_b32 v134, v86, v87 offset0:168 offset1:236
	ds_write2_b32 v135, v94, v95 offset0:184 offset1:252
	ds_write2_b32 v139, v90, v91 offset0:72 offset1:140
.LBB0_197:
	s_or_b64 exec, exec, s[16:17]
	s_nop 2
	ds_read_b128 v[84:87], v137 offset:14848
	v_add_u32_e32 v140, 0x9600, v3
	s_waitcnt lgkmcnt(0)
	v_mfma_f32_16x16x32_bf16 v[76:79], v[76:79], v[84:87], 0
	ds_read_b128 v[84:87], v137 offset:14912
	s_waitcnt lgkmcnt(0)
	v_mfma_f32_16x16x32_bf16 v[76:79], v[80:83], v[84:87], v[76:79]
	ds_read_b128 v[80:83], v138 offset:2560
	s_waitcnt lgkmcnt(0)
	v_mfma_f32_16x16x32_bf16 v[72:75], v[72:75], v[80:83], 0
	ds_read_b128 v[80:83], v138 offset:7680
	s_waitcnt lgkmcnt(0)
	v_mfma_f32_16x16x32_bf16 v[68:71], v[68:71], v[80:83], 0
	s_and_saveexec_b64 s[16:17], s[14:15]
	s_cbranch_execz .LBB0_199
	s_nop 2
	ds_write2_b32 v134, v72, v73 offset0:48 offset1:116
	s_nop 1
	ds_write2_b32 v135, v68, v69 offset0:64 offset1:132
	ds_write2_b32 v136, v76, v77 offset0:80 offset1:148
	ds_write2_b32 v134, v74, v75 offset0:184 offset1:252
	ds_write2_b32 v140, v70, v71 offset0:72 offset1:140
	ds_write2_b32 v139, v78, v79 offset0:88 offset1:156

; #define LAS __attribute__((address_space(3)))
; __device__ __forceinline__ unsigned pk2(float lo, float hi) { const f32x2 v = {lo, hi}; const bf16x2n b = __builtin_convertvector(v, bf16x2n); return __builtin_bit_cast(unsigned, b); }
; __device__ __forceinline__ float sigmoidf_(float x) { return rcp_(1.0f + __expf(-x)); }
; __device__ __forceinline__ void rwkv_block(KP p, int o, int b, int hd, LAS unsigned char* lds, const bf16_t* P, bf16_t* YB) {
;     ...
;                 f32x4 la, lb;
;                 cv = unpack4((u32x2){d.l[1].x, d.l[1].y}); pv = unpack4((u32x2){d.l[0].x, d.l[0].y}); la = cv + mu_la * (pv - cv);
;                 cv = unpack4((u32x2){d.l[1].z, d.l[1].w}); pv = unpack4((u32x2){d.l[0].z, d.l[0].w}); lb = cv + mu_lb * (pv - cv);
;                 float o8[8];
; #pragma unroll
;                 for (int i = 0; i < 4; ++i) {
;                     const float sa = sigmoidf_(lsc * la[i]), sb = sigmoidf_(lsc * lb[i]);
;                     o8[i] = jg < 4 ? 2.0f * sa - 1.0f : (jg < 8 ? la[i] : sa);
;                     o8[4 + i] = jg < 4 ? 2.0f * sb - 1.0f : (jg < 8 ? lb[i] : sb);
;                 }
;                 u32x4 w; w.x = pk2(o8[0], o8[1]); w.y = pk2(o8[2], o8[3]); w.z = pk2(o8[4], o8[5]); w.w = pk2(o8[6], o8[7]);
;                 *(LAS u32x4*)(Lin + t4 * 136 + 8 * jg) = w;
;             }
;             LDS_WAIT(); asm volatile("" ::: "memory");
; #pragma unroll
;             for (int ct = 0; ct < 4; ++ct) {
;                 f32x4 c0 = {0.f, 0.f, 0.f, 0.f}, c1 = {0.f, 0.f, 0.f, 0.f}, c2 = {0.f, 0.f, 0.f, 0.f};
;                 c0 = mfma16(*(const LAS bf16x8*)(Lin + fr * 136 + fq * 8), *(const LAS bf16x8*)(wBt + (ct * 16 + fr) * 40 + fq * 8), c0);
;                 c1 = mfma16(*(const LAS bf16x8*)(Lin + fr * 136 + 32 + fq * 8), *(const LAS bf16x8*)(aBt + (ct * 16 + fr) * 40 + fq * 8), c1);
; #pragma unroll
;                 for (int kb = 0; kb < 2; ++kb)
;                     c2 = mfma16(*(const LAS bf16x8*)(Lin + fr * 136 + 64 + kb * 32 + fq * 8), *(const LAS bf16x8*)(gBt + (ct * 16 + fr) * 72 + kb * 32 + fq * 8), c2);
;                 if (fq == 0) {
; #pragma unroll
;                     for (int jj = 0; jj < 4; ++jj) { Lout[jj * 68 + ct * 16 + fr] = c0[jj]; Lout[272 + jj * 68 + ct * 16 + fr] = c1[jj]; Lout[544 + jj * 68 + ct * 16 + fr] = c2[jj]; }
;                 }
;             }
.LBB0_208:
	s_waitcnt vmcnt(9)
	v_lshlrev_b32_e32 v0, 16, v60
	v_lshlrev_b32_e32 v70, 16, v64
	v_lshlrev_b32_e32 v74, 16, v62
	v_lshlrev_b32_e32 v78, 16, v66
	v_sub_f32_e32 v70, v70, v0
	v_sub_f32_e32 v78, v78, v74
	v_fmac_f32_e32 v0, v16, v70
	v_fmac_f32_e32 v74, v28, v78
	v_mul_f32_e32 v70, v103, v0
	v_mul_f32_e32 v78, v103, v74
	v_mul_f32_e32 v70, 0xbfb8aa3b, v70
	v_mul_f32_e32 v78, 0xbfb8aa3b, v78
	v_exp_f32_e32 v70, v70
	v_exp_f32_e32 v78, v78
	v_and_b32_e32 v3, 0xffff0000, v60
	v_and_b32_e32 v71, 0xffff0000, v64
	v_add_f32_e32 v70, 1.0, v70
	v_add_f32_e32 v78, 1.0, v78
	v_rcp_f32_e32 v70, v70
	v_rcp_f32_e32 v78, v78
	v_and_b32_e32 v75, 0xffff0000, v62
	v_and_b32_e32 v79, 0xffff0000, v66
	v_sub_f32_e32 v71, v71, v3
	v_sub_f32_e32 v79, v79, v75
	v_fmac_f32_e32 v3, v17, v71
	v_fmac_f32_e32 v75, v29, v79
	v_fma_f32 v82, v70, 2.0, -1.0
	v_cndmask_b32_e64 v0, v70, v0, s[12:13]
	v_fma_f32 v70, v78, 2.0, -1.0
	v_cndmask_b32_e64 v74, v78, v74, s[12:13]
	v_mul_f32_e32 v71, v103, v3
	v_mul_f32_e32 v78, v103, v75
	v_mul_f32_e32 v71, 0xbfb8aa3b, v71
	v_mul_f32_e32 v78, 0xbfb8aa3b, v78
	v_exp_f32_e32 v71, v71
	v_exp_f32_e32 v78, v78
	v_lshlrev_b32_e32 v68, 16, v61
	v_lshlrev_b32_e32 v72, 16, v65
	v_sub_f32_e32 v72, v72, v68
	v_fmac_f32_e32 v68, v18, v72
	v_add_f32_e32 v71, 1.0, v71
	v_cndmask_b32_e64 v70, v74, v70, s[10:11]
	v_add_f32_e32 v74, 1.0, v78
	v_mul_f32_e32 v72, v103, v68
	v_rcp_f32_e32 v71, v71
	v_rcp_f32_e32 v74, v74
	v_mul_f32_e32 v72, 0xbfb8aa3b, v72
	v_lshlrev_b32_e32 v76, 16, v63
	v_lshlrev_b32_e32 v80, 16, v67
	v_exp_f32_e32 v72, v72
	v_sub_f32_e32 v80, v80, v76
	v_fmac_f32_e32 v76, v30, v80
	v_fma_f32 v78, v71, 2.0, -1.0
	v_cndmask_b32_e64 v3, v71, v3, s[12:13]
	v_fma_f32 v71, v74, 2.0, -1.0
	v_cndmask_b32_e64 v74, v74, v75, s[12:13]
	v_mul_f32_e32 v75, v103, v76
	v_mul_f32_e32 v75, 0xbfb8aa3b, v75
	v_add_f32_e32 v72, 1.0, v72
	v_exp_f32_e32 v75, v75
	v_rcp_f32_e32 v72, v72
	v_and_b32_e32 v69, 0xffff0000, v61
	v_and_b32_e32 v73, 0xffff0000, v65
	v_and_b32_e32 v77, 0xffff0000, v63
	v_and_b32_e32 v81, 0xffff0000, v67
	v_sub_f32_e32 v73, v73, v69
	v_sub_f32_e32 v81, v81, v77
	v_cndmask_b32_e64 v71, v74, v71, s[10:11]
	v_add_f32_e32 v74, 1.0, v75
	v_fma_f32 v75, v72, 2.0, -1.0
	v_cndmask_b32_e64 v68, v72, v68, s[12:13]
	v_fmac_f32_e32 v69, v19, v73
	v_fmac_f32_e32 v77, v31, v81
	v_cndmask_b32_e64 v72, v68, v75, s[10:11]
	v_mul_f32_e32 v73, v103, v69
	v_mul_f32_e32 v75, v103, v77
	v_rcp_f32_e32 v74, v74
	v_mul_f32_e32 v73, 0xbfb8aa3b, v73
	v_mul_f32_e32 v75, 0xbfb8aa3b, v75
	v_exp_f32_e32 v73, v73
	v_exp_f32_e32 v75, v75
	v_fma_f32 v68, v74, 2.0, -1.0
	v_cndmask_b32_e64 v74, v74, v76, s[12:13]
	v_add_f32_e32 v73, 1.0, v73
	v_cndmask_b32_e64 v74, v74, v68, s[10:11]
	v_add_f32_e32 v68, 1.0, v75
	v_rcp_f32_e32 v73, v73
	v_rcp_f32_e32 v68, v68
	v_cndmask_b32_e64 v0, v0, v82, s[10:11]
	v_cndmask_b32_e64 v3, v3, v78, s[10:11]
	v_fma_f32 v75, v73, 2.0, -1.0
	v_cndmask_b32_e64 v69, v73, v69, s[12:13]
	v_fma_f32 v73, v68, 2.0, -1.0
	v_cndmask_b32_e64 v68, v68, v77, s[12:13]
	v_cndmask_b32_e64 v69, v69, v75, s[10:11]
	v_cndmask_b32_e64 v73, v68, v73, s[10:11]
	v_cvt_pk_bf16_f32 v68, v0, v3
	v_cvt_pk_bf16_f32 v69, v72, v69
	v_cvt_pk_bf16_f32 v70, v70, v71
	v_cvt_pk_bf16_f32 v71, v74, v73
	ds_write_b128 v132, v[68:71] offset:19456
	s_waitcnt lgkmcnt(0)
	ds_read_b128 v[80:83], v133 offset:19584
	ds_read_b128 v[76:79], v133 offset:19648
	ds_read_b128 v[68:71], v163 offset:10240
	ds_read_b128 v[84:87], v163 offset:10304
	s_waitcnt lgkmcnt(1)
	v_mfma_f32_16x16x32_bf16 v[88:91], v[80:83], v[68:71], 0
	ds_read_b128 v[72:75], v133 offset:19456
	ds_read_b128 v[68:71], v133 offset:19520
	s_waitcnt lgkmcnt(2)
	v_mfma_f32_16x16x32_bf16 v[84:87], v[76:79], v[84:87], v[88:91]
	s_nop 3
	ds_read_b128 v[88:91], v162
	ds_read_b128 v[92:95], v162 offset:5120
	s_waitcnt lgkmcnt(1)
	v_mfma_f32_16x16x32_bf16 v[88:91], v[72:75], v[88:91], 0
	s_waitcnt lgkmcnt(0)
	v_mfma_f32_16x16x32_bf16 v[92:95], v[68:71], v[92:95], 0
	s_and_saveexec_b64 s[18:19], s[14:15]
	s_cbranch_execz .LBB0_210
	s_nop 3
	ds_write2_b32 v134, v88, v89 offset1:68
	s_nop 0
	ds_write2_b32 v135, v92, v93 offset0:16 offset1:84
	ds_write2_b32 v136, v84, v85 offset0:32 offset1:100
	ds_write2_b32 v134, v90, v91 offset0:136 offset1:204
	ds_write2_b32 v135, v94, v95 offset0:152 offset1:220
	ds_write2_b32 v136, v86, v87 offset0:168 offset1:236
; #define LAS __attribute__((address_space(3)))
; __device__ __forceinline__ f32x4 mfma16(bf16x8 a, bf16x8 b, f32x4 c) { return __builtin_amdgcn_mfma_f32_16x16x32_bf16(a, b, c, 0, 0, 0); }
; __device__ __forceinline__ void rwkv_block(KP p, int o, int b, int hd, LAS unsigned char* lds, const bf16_t* P, bf16_t* YB) {
;     ...
;             for (int ct = 0; ct < 4; ++ct) {
;                 f32x4 c0 = {0.f, 0.f, 0.f, 0.f}, c1 = {0.f, 0.f, 0.f, 0.f}, c2 = {0.f, 0.f, 0.f, 0.f};
;                 c0 = mfma16(*(const LAS bf16x8*)(Lin + fr * 136 + fq * 8), *(const LAS bf16x8*)(wBt + (ct * 16 + fr) * 40 + fq * 8), c0);
;                 c1 = mfma16(*(const LAS bf16x8*)(Lin + fr * 136 + 32 + fq * 8), *(const LAS bf16x8*)(aBt + (ct * 16 + fr) * 40 + fq * 8), c1);
; #pragma unroll
;                 for (int kb = 0; kb < 2; ++kb)
;                     c2 = mfma16(*(const LAS bf16x8*)(Lin + fr * 136 + 64 + kb * 32 + fq * 8), *(const LAS bf16x8*)(gBt + (ct * 16 + fr) * 72 + kb * 32 + fq * 8), c2);
;                 if (fq == 0) {
; #pragma unroll
;                     for (int jj = 0; jj < 4; ++jj) { Lout[jj * 68 + ct * 16 + fr] = c0[jj]; Lout[272 + jj * 68 + ct * 16 + fr] = c1[jj]; Lout[544 + jj * 68 + ct * 16 + fr] = c2[jj]; }
;                 }
;             }
.LBB0_210:
	s_or_b64 exec, exec, s[18:19]
	ds_read_b128 v[84:87], v137 offset:10240
	s_nop 1
	ds_read_b128 v[88:91], v137 offset:10304
	s_waitcnt lgkmcnt(1)
	v_mfma_f32_16x16x32_bf16 v[84:87], v[80:83], v[84:87], 0
	s_waitcnt lgkmcnt(0)
	v_mfma_f32_16x16x32_bf16 v[84:87], v[76:79], v[88:91], v[84:87]
	ds_read_b128 v[88:91], v138
	ds_read_b128 v[92:95], v138 offset:5120
	s_waitcnt lgkmcnt(1)
	v_mfma_f32_16x16x32_bf16 v[88:91], v[72:75], v[88:91], 0
	s_waitcnt lgkmcnt(0)
	v_mfma_f32_16x16x32_bf16 v[92:95], v[68:71], v[92:95], 0
	s_and_saveexec_b64 s[18:19], s[14:15]
	s_cbranch_execz .LBB0_212
	s_nop 3
	ds_write2_b32 v134, v88, v89 offset0:16 offset1:84
	s_nop 0
	ds_write2_b32 v135, v92, v93 offset0:32 offset1:100
	ds_write2_b32 v136, v84, v85 offset0:48 offset1:116
	ds_write2_b32 v134, v90, v91 offset0:152 offset1:220
	ds_write2_b32 v135, v94, v95 offset0:168 offset1:236
	ds_write2_b32 v136, v86, v87 offset0:184 offset1:252
.LBB0_212:
	s_or_b64 exec, exec, s[18:19]
	ds_read_b128 v[84:87], v137 offset:12544
	s_nop 1
	ds_read_b128 v[88:91], v137 offset:12608
	s_waitcnt lgkmcnt(1)
	v_mfma_f32_16x16x32_bf16 v[84:87], v[80:83], v[84:87], 0
	s_waitcnt lgkmcnt(0)
	v_mfma_f32_16x16x32_bf16 v[84:87], v[76:79], v[88:91], v[84:87]
	ds_read_b128 v[88:91], v138 offset:1280
	ds_read_b128 v[92:95], v138 offset:6400
	s_waitcnt lgkmcnt(1)
	v_mfma_f32_16x16x32_bf16 v[88:91], v[72:75], v[88:91], 0
	s_waitcnt lgkmcnt(0)
	v_mfma_f32_16x16x32_bf16 v[92:95], v[68:71], v[92:95], 0
	s_and_saveexec_b64 s[18:19], s[14:15]
	s_cbranch_execz .LBB0_214
	s_nop 3
	ds_write2_b32 v134, v88, v89 offset0:32 offset1:100
	s_nop 0
	ds_write2_b32 v135, v92, v93 offset0:48 offset1:116
	ds_write2_b32 v136, v84, v85 offset0:64 offset1:132
	ds_write2_b32 v134, v90, v91 offset0:168 offset1:236
	ds_write2_b32 v135, v94, v95 offset0:184 offset1:252
	ds_write2_b32 v139, v86, v87 offset0:72 offset1:140
.LBB0_214:
	s_or_b64 exec, exec, s[18:19]
	ds_read_b128 v[84:87], v137 offset:14848
	s_waitcnt lgkmcnt(0)
	v_mfma_f32_16x16x32_bf16 v[80:83], v[80:83], v[84:87], 0
	ds_read_b128 v[84:87], v137 offset:14912
	s_waitcnt lgkmcnt(0)
	v_mfma_f32_16x16x32_bf16 v[76:79], v[76:79], v[84:87], v[80:83]
	s_nop 4
	ds_read_b128 v[80:83], v138 offset:2560
	s_waitcnt lgkmcnt(0)
	v_mfma_f32_16x16x32_bf16 v[72:75], v[72:75], v[80:83], 0
	ds_read_b128 v[80:83], v138 offset:7680
	s_waitcnt lgkmcnt(0)
	v_mfma_f32_16x16x32_bf16 v[68:71], v[68:71], v[80:83], 0
	s_and_saveexec_b64 s[18:19], s[14:15]
	s_cbranch_execz .LBB0_216
	s_nop 2
	ds_write2_b32 v134, v72, v73 offset0:48 offset1:116
	s_nop 1
	ds_write2_b32 v135, v68, v69 offset0:64 offset1:132
	ds_write2_b32 v136, v76, v77 offset0:80 offset1:148
	ds_write2_b32 v134, v74, v75 offset0:184 offset1:252
	ds_write2_b32 v140, v70, v71 offset0:72 offset1:140
	ds_write2_b32 v139, v78, v79 offset0:88 offset1:156

; #define LAS __attribute__((address_space(3)))
; __device__ __forceinline__ void rwkv_block(KP p, int o, int b, int hd, LAS unsigned char* lds, const bf16_t* P, bf16_t* YB) {
;     ...
;                 f32x4 la, lb;
;                 cv = unpack4((u32x2){d.l[1].x, d.l[1].y}); pv = unpack4((u32x2){d.l[0].x, d.l[0].y}); la = cv + mu_la * (pv - cv);
;                 cv = unpack4((u32x2){d.l[1].z, d.l[1].w}); pv = unpack4((u32x2){d.l[0].z, d.l[0].w}); lb = cv + mu_lb * (pv - cv);
;                 float o8[8];
; #pragma unroll
;                 for (int i = 0; i < 4; ++i) {
;                     const float sa = sigmoidf_(lsc * la[i]), sb = sigmoidf_(lsc * lb[i]);
;                     o8[i] = jg < 4 ? 2.0f * sa - 1.0f : (jg < 8 ? la[i] : sa);
;                     o8[4 + i] = jg < 4 ? 2.0f * sb - 1.0f : (jg < 8 ? lb[i] : sb);
;                 }
;                 u32x4 w; w.x = pk2(o8[0], o8[1]); w.y = pk2(o8[2], o8[3]); w.z = pk2(o8[4], o8[5]); w.w = pk2(o8[6], o8[7]);
;                 *(LAS u32x4*)(Lin + t4 * 136 + 8 * jg) = w;
;             }
;             LDS_WAIT(); asm volatile("" ::: "memory");
; #pragma unroll
;             for (int ct = 0; ct < 4; ++ct) {
;                 f32x4 c0 = {0.f, 0.f, 0.f, 0.f}, c1 = {0.f, 0.f, 0.f, 0.f}, c2 = {0.f, 0.f, 0.f, 0.f};
;                 c0 = mfma16(*(const LAS bf16x8*)(Lin + fr * 136 + fq * 8), *(const LAS bf16x8*)(wBt + (ct * 16 + fr) * 40 + fq * 8), c0);
;     ...
;         auto outp = [&](int m) {
;             LAS float* B = (LAS float*)(lds + BUF0 + (m & 1) * BUFSZ);
;             LAS float* Vv = B + 5120; LAS float* Gg = B + 6144; LAS float* Yy = B + 7168; LAS float* Bon = B + 8192;
;             const int tt = 4 * q + t4; const size_t row = rbase + m * 16 + tt;
;             const f32x4 y = *(const LAS f32x4*)(Yy + tt * 64 + 4 * jg);
;             const float mean = red16((y.x + y.y) + (y.z + y.w)) * (1.f / 64.f);
;             const f32x4 dd = y - mean;
;             const float var = red16((dd.x * dd.x + dd.y * dd.y) + (dd.z * dd.z + dd.w * dd.w)) * (1.f / 64.f);
;             const f32x4 yn = dd * __builtin_amdgcn_rsqf(var + 64e-5f) * lng + lnb;
;             const f32x4 ov = (yn + Bon[tt] * *(const LAS f32x4*)(Vv + tt * 64 + 4 * jg)) * *(const LAS f32x4*)(Gg + tt * 64 + 4 * jg);
;             u32x2 w; w.x = pk2(ov.x, ov.y); w.y = pk2(ov.z, ov.w);
;             *(u32x2*)(YB + row * DM + ch0) = w;
.LBB0_220:
	ds_read_b128 v[68:71], v161
	s_andn2_b64 vcc, exec, s[26:27]
	s_waitcnt lgkmcnt(0)
	v_mov_b32_e32 v72, v69
	v_mov_b32_e32 v73, v70
	v_mov_b32_e32 v74, v68
	v_mov_b32_e32 v75, v71
	v_pk_add_f32 v[72:73], v[72:73], v[74:75]
	s_nop 0
	v_add_f32_e32 v0, v72, v73
	s_nop 1
	v_add_f32_dpp v0, v0, v0 quad_perm:[1,0,3,2] row_mask:0xf bank_mask:0xf bound_ctrl:1
	s_nop 1
	v_add_f32_dpp v0, v0, v0 quad_perm:[2,3,0,1] row_mask:0xf bank_mask:0xf bound_ctrl:1
	s_nop 1
	v_add_f32_dpp v0, v0, v0 row_half_mirror row_mask:0xf bank_mask:0xf bound_ctrl:1
	s_nop 1
	v_add_f32_dpp v0, v0, v0 row_mirror row_mask:0xf bank_mask:0xf bound_ctrl:1
	v_fmamk_f32 v69, v0, 0xbc800000, v69
	v_fmamk_f32 v68, v0, 0xbc800000, v68
	v_fmamk_f32 v71, v0, 0xbc800000, v71
	v_fmac_f32_e32 v70, 0xbc800000, v0
	v_pk_mul_f32 v[72:73], v[70:71], v[70:71]
	v_pk_mul_f32 v[74:75], v[68:69], v[68:69]
	s_nop 0
	v_pk_mov_b32 v[76:77], v[74:75], v[72:73] op_sel:[1,0]
	v_mov_b32_e32 v75, v73
	v_pk_add_f32 v[72:73], v[76:77], v[74:75]
	s_nop 0
	v_add_f32_e32 v0, v72, v73
	s_nop 1
	v_add_f32_dpp v0, v0, v0 quad_perm:[1,0,3,2] row_mask:0xf bank_mask:0xf bound_ctrl:1
	s_nop 1
	v_add_f32_dpp v0, v0, v0 quad_perm:[2,3,0,1] row_mask:0xf bank_mask:0xf bound_ctrl:1
	s_nop 1
	v_add_f32_dpp v0, v0, v0 row_half_mirror row_mask:0xf bank_mask:0xf bound_ctrl:1
	s_nop 1
	v_add_f32_dpp v0, v0, v0 row_mirror row_mask:0xf bank_mask:0xf bound_ctrl:1
	v_fmamk_f32 v0, v0, 0x3c800000, v227
	v_rsq_f32_e32 v0, v0
	s_nop 0
	v_pk_mul_f32 v[68:69], v[68:69], v[0:1] op_sel_hi:[1,0]
	v_pk_mul_f32 v[70:71], v[70:71], v[0:1] op_sel_hi:[1,0]
	v_pk_fma_f32 v[74:75], v[12:13], v[68:69], v[20:21]
	v_pk_fma_f32 v[72:73], v[14:15], v[70:71], v[22:23]
	ds_read_b32 v0, v152
	ds_read_b128 v[68:71], v153
	s_waitcnt lgkmcnt(0)
	v_pk_fma_f32 v[74:75], v[68:69], v[0:1], v[74:75] op_sel_hi:[1,0,1]
	v_pk_fma_f32 v[72:73], v[70:71], v[0:1], v[72:73] op_sel_hi:[1,0,1]
	ds_read_b128 v[68:71], v154
	s_waitcnt lgkmcnt(0)
	v_pk_mul_f32 v[70:71], v[70:71], v[72:73]
	v_pk_mul_f32 v[68:69], v[68:69], v[74:75]
	s_nop 0
	v_cvt_pk_bf16_f32 v68, v68, v69
	v_cvt_pk_bf16_f32 v69, v70, v71
	global_store_dwordx2 v[130:131], v[68:69], off
	s_waitcnt lgkmcnt(0)
	s_cbranch_vccnz .LBB0_203
	s_waitcnt vmcnt(9)
	v_lshlrev_b32_e32 v0, 16, v52
	v_lshlrev_b32_e32 v70, 16, v56
	v_lshlrev_b32_e32 v74, 16, v54
	v_lshlrev_b32_e32 v78, 16, v58
	v_sub_f32_e32 v70, v70, v0
	v_sub_f32_e32 v78, v78, v74
	v_fmac_f32_e32 v0, v16, v70
	v_fmac_f32_e32 v74, v28, v78
	v_mul_f32_e32 v70, v103, v0
	v_mul_f32_e32 v78, v103, v74
	v_mul_f32_e32 v70, 0xbfb8aa3b, v70
	v_mul_f32_e32 v78, 0xbfb8aa3b, v78
	v_exp_f32_e32 v70, v70
	v_exp_f32_e32 v78, v78
	v_and_b32_e32 v3, 0xffff0000, v52
	v_and_b32_e32 v71, 0xffff0000, v56
	v_add_f32_e32 v70, 1.0, v70
	v_add_f32_e32 v78, 1.0, v78
	v_rcp_f32_e32 v70, v70
	v_rcp_f32_e32 v78, v78
	v_and_b32_e32 v75, 0xffff0000, v54
	v_and_b32_e32 v79, 0xffff0000, v58
	v_sub_f32_e32 v71, v71, v3
	v_sub_f32_e32 v79, v79, v75
	v_fmac_f32_e32 v3, v17, v71
	v_fmac_f32_e32 v75, v29, v79
	v_fma_f32 v82, v70, 2.0, -1.0
	v_cndmask_b32_e64 v0, v70, v0, s[12:13]
	v_fma_f32 v70, v78, 2.0, -1.0
	v_cndmask_b32_e64 v74, v78, v74, s[12:13]
	v_mul_f32_e32 v71, v103, v3
	v_mul_f32_e32 v78, v103, v75
	v_mul_f32_e32 v71, 0xbfb8aa3b, v71
	v_mul_f32_e32 v78, 0xbfb8aa3b, v78
	v_exp_f32_e32 v71, v71
	v_exp_f32_e32 v78, v78
	v_lshlrev_b32_e32 v68, 16, v53
	v_lshlrev_b32_e32 v72, 16, v57
	v_sub_f32_e32 v72, v72, v68
	v_fmac_f32_e32 v68, v18, v72
	v_add_f32_e32 v71, 1.0, v71
	v_cndmask_b32_e64 v70, v74, v70, s[10:11]
	v_add_f32_e32 v74, 1.0, v78
	v_mul_f32_e32 v72, v103, v68
	v_rcp_f32_e32 v71, v71
	v_rcp_f32_e32 v74, v74
	v_mul_f32_e32 v72, 0xbfb8aa3b, v72
	v_lshlrev_b32_e32 v76, 16, v55
	v_lshlrev_b32_e32 v80, 16, v59
	v_exp_f32_e32 v72, v72
	v_sub_f32_e32 v80, v80, v76
	v_fmac_f32_e32 v76, v30, v80
	v_fma_f32 v78, v71, 2.0, -1.0
	v_cndmask_b32_e64 v3, v71, v3, s[12:13]
	v_fma_f32 v71, v74, 2.0, -1.0
	v_cndmask_b32_e64 v74, v74, v75, s[12:13]
	v_mul_f32_e32 v75, v103, v76
	v_mul_f32_e32 v75, 0xbfb8aa3b, v75
	v_add_f32_e32 v72, 1.0, v72
	v_exp_f32_e32 v75, v75
	v_rcp_f32_e32 v72, v72
	v_and_b32_e32 v69, 0xffff0000, v53
	v_and_b32_e32 v73, 0xffff0000, v57
	v_and_b32_e32 v77, 0xffff0000, v55
	v_and_b32_e32 v81, 0xffff0000, v59
	v_sub_f32_e32 v73, v73, v69
	v_sub_f32_e32 v81, v81, v77
	v_cndmask_b32_e64 v71, v74, v71, s[10:11]
	v_add_f32_e32 v74, 1.0, v75
	v_fma_f32 v75, v72, 2.0, -1.0
	v_cndmask_b32_e64 v68, v72, v68, s[12:13]
	v_fmac_f32_e32 v69, v19, v73
	v_fmac_f32_e32 v77, v31, v81
	v_cndmask_b32_e64 v72, v68, v75, s[10:11]
	v_mul_f32_e32 v73, v103, v69
	v_mul_f32_e32 v75, v103, v77
	v_rcp_f32_e32 v74, v74
	v_mul_f32_e32 v73, 0xbfb8aa3b, v73
	v_mul_f32_e32 v75, 0xbfb8aa3b, v75
	v_exp_f32_e32 v73, v73
	v_exp_f32_e32 v75, v75
	v_fma_f32 v68, v74, 2.0, -1.0
	v_cndmask_b32_e64 v74, v74, v76, s[12:13]
	v_add_f32_e32 v73, 1.0, v73
	v_cndmask_b32_e64 v74, v74, v68, s[10:11]
	v_add_f32_e32 v68, 1.0, v75
	v_rcp_f32_e32 v73, v73
	v_rcp_f32_e32 v68, v68
	v_cndmask_b32_e64 v0, v0, v82, s[10:11]
	v_cndmask_b32_e64 v3, v3, v78, s[10:11]
	v_fma_f32 v75, v73, 2.0, -1.0
	v_cndmask_b32_e64 v69, v73, v69, s[12:13]
	v_fma_f32 v73, v68, 2.0, -1.0
	v_cndmask_b32_e64 v68, v68, v77, s[12:13]
	v_cndmask_b32_e64 v69, v69, v75, s[10:11]
	v_cndmask_b32_e64 v73, v68, v73, s[10:11]
	v_cvt_pk_bf16_f32 v68, v0, v3
	v_cvt_pk_bf16_f32 v69, v72, v69
	v_cvt_pk_bf16_f32 v70, v70, v71
	v_cvt_pk_bf16_f32 v71, v74, v73
	ds_write_b128 v132, v[68:71] offset:19456
	s_waitcnt lgkmcnt(0)
	ds_read_b128 v[80:83], v133 offset:19584
	ds_read_b128 v[76:79], v133 offset:19648
	ds_read_b128 v[68:71], v163 offset:10240
	ds_read_b128 v[84:87], v163 offset:10304
	s_waitcnt lgkmcnt(1)
	v_mfma_f32_16x16x32_bf16 v[88:91], v[80:83], v[68:71], 0
	ds_read_b128 v[72:75], v133 offset:19456
	ds_read_b128 v[68:71], v133 offset:19520
	s_waitcnt lgkmcnt(2)
	v_mfma_f32_16x16x32_bf16 v[84:87], v[76:79], v[84:87], v[88:91]
	s_nop 3
	ds_read_b128 v[88:91], v162
	ds_read_b128 v[92:95], v162 offset:5120
	s_waitcnt lgkmcnt(1)
	v_mfma_f32_16x16x32_bf16 v[88:91], v[72:75], v[88:91], 0
	s_waitcnt lgkmcnt(0)
	v_mfma_f32_16x16x32_bf16 v[92:95], v[68:71], v[92:95], 0
	s_and_saveexec_b64 s[18:19], s[14:15]
	s_cbranch_execz .LBB0_223
	s_nop 3
	ds_write2_b32 v134, v88, v89 offset1:68
	s_nop 0
	ds_write2_b32 v135, v92, v93 offset0:16 offset1:84
	ds_write2_b32 v136, v84, v85 offset0:32 offset1:100
	ds_write2_b32 v134, v90, v91 offset0:136 offset1:204
	ds_write2_b32 v135, v94, v95 offset0:152 offset1:220
	ds_write2_b32 v136, v86, v87 offset0:168 offset1:236
; #define LAS __attribute__((address_space(3)))
; __device__ __forceinline__ f32x4 mfma16(bf16x8 a, bf16x8 b, f32x4 c) { return __builtin_amdgcn_mfma_f32_16x16x32_bf16(a, b, c, 0, 0, 0); }
; __device__ __forceinline__ void rwkv_block(KP p, int o, int b, int hd, LAS unsigned char* lds, const bf16_t* P, bf16_t* YB) {
;     ...
;             for (int ct = 0; ct < 4; ++ct) {
;                 f32x4 c0 = {0.f, 0.f, 0.f, 0.f}, c1 = {0.f, 0.f, 0.f, 0.f}, c2 = {0.f, 0.f, 0.f, 0.f};
;                 c0 = mfma16(*(const LAS bf16x8*)(Lin + fr * 136 + fq * 8), *(const LAS bf16x8*)(wBt + (ct * 16 + fr) * 40 + fq * 8), c0);
;                 c1 = mfma16(*(const LAS bf16x8*)(Lin + fr * 136 + 32 + fq * 8), *(const LAS bf16x8*)(aBt + (ct * 16 + fr) * 40 + fq * 8), c1);
; #pragma unroll
;                 for (int kb = 0; kb < 2; ++kb)
;                     c2 = mfma16(*(const LAS bf16x8*)(Lin + fr * 136 + 64 + kb * 32 + fq * 8), *(const LAS bf16x8*)(gBt + (ct * 16 + fr) * 72 + kb * 32 + fq * 8), c2);
;                 if (fq == 0) {
; #pragma unroll
;                     for (int jj = 0; jj < 4; ++jj) { Lout[jj * 68 + ct * 16 + fr] = c0[jj]; Lout[272 + jj * 68 + ct * 16 + fr] = c1[jj]; Lout[544 + jj * 68 + ct * 16 + fr] = c2[jj]; }
;                 }
;             }
.LBB0_223:
	s_or_b64 exec, exec, s[18:19]
	ds_read_b128 v[84:87], v137 offset:10240
	s_nop 1
	ds_read_b128 v[88:91], v137 offset:10304
	s_waitcnt lgkmcnt(1)
	v_mfma_f32_16x16x32_bf16 v[84:87], v[80:83], v[84:87], 0
	s_waitcnt lgkmcnt(0)
	v_mfma_f32_16x16x32_bf16 v[84:87], v[76:79], v[88:91], v[84:87]
	ds_read_b128 v[88:91], v138
	ds_read_b128 v[92:95], v138 offset:5120
	s_waitcnt lgkmcnt(1)
	v_mfma_f32_16x16x32_bf16 v[88:91], v[72:75], v[88:91], 0
	s_waitcnt lgkmcnt(0)
	v_mfma_f32_16x16x32_bf16 v[92:95], v[68:71], v[92:95], 0
	s_and_saveexec_b64 s[18:19], s[14:15]
	s_cbranch_execz .LBB0_225
	s_nop 3
	ds_write2_b32 v134, v88, v89 offset0:16 offset1:84
	s_nop 0
	ds_write2_b32 v135, v92, v93 offset0:32 offset1:100
	ds_write2_b32 v136, v84, v85 offset0:48 offset1:116
	ds_write2_b32 v134, v90, v91 offset0:152 offset1:220
	ds_write2_b32 v135, v94, v95 offset0:168 offset1:236
	ds_write2_b32 v136, v86, v87 offset0:184 offset1:252
.LBB0_225:
	s_or_b64 exec, exec, s[18:19]
	ds_read_b128 v[84:87], v137 offset:12544
	s_nop 1
	ds_read_b128 v[88:91], v137 offset:12608
	s_waitcnt lgkmcnt(1)
	v_mfma_f32_16x16x32_bf16 v[84:87], v[80:83], v[84:87], 0
	s_waitcnt lgkmcnt(0)
	v_mfma_f32_16x16x32_bf16 v[84:87], v[76:79], v[88:91], v[84:87]
	ds_read_b128 v[88:91], v138 offset:1280
	ds_read_b128 v[92:95], v138 offset:6400
	s_waitcnt lgkmcnt(1)
	v_mfma_f32_16x16x32_bf16 v[88:91], v[72:75], v[88:91], 0
	s_waitcnt lgkmcnt(0)
	v_mfma_f32_16x16x32_bf16 v[92:95], v[68:71], v[92:95], 0
	s_and_saveexec_b64 s[18:19], s[14:15]
	s_cbranch_execz .LBB0_227
	s_nop 3
	ds_write2_b32 v134, v88, v89 offset0:32 offset1:100
	s_nop 0
	ds_write2_b32 v135, v92, v93 offset0:48 offset1:116
	ds_write2_b32 v136, v84, v85 offset0:64 offset1:132
	ds_write2_b32 v134, v90, v91 offset0:168 offset1:236
	ds_write2_b32 v135, v94, v95 offset0:184 offset1:252
	ds_write2_b32 v139, v86, v87 offset0:72 offset1:140
.LBB0_227:
	s_or_b64 exec, exec, s[18:19]
	ds_read_b128 v[84:87], v137 offset:14848
	s_waitcnt lgkmcnt(0)
	v_mfma_f32_16x16x32_bf16 v[80:83], v[80:83], v[84:87], 0
	ds_read_b128 v[84:87], v137 offset:14912
	s_waitcnt lgkmcnt(0)
	v_mfma_f32_16x16x32_bf16 v[76:79], v[76:79], v[84:87], v[80:83]
	s_nop 4
	ds_read_b128 v[80:83], v138 offset:2560
	s_waitcnt lgkmcnt(0)
	v_mfma_f32_16x16x32_bf16 v[72:75], v[72:75], v[80:83], 0
	ds_read_b128 v[80:83], v138 offset:7680
	s_waitcnt lgkmcnt(0)
	v_mfma_f32_16x16x32_bf16 v[68:71], v[68:71], v[80:83], 0
	s_and_saveexec_b64 s[18:19], s[14:15]
	s_cbranch_execz .LBB0_229
	s_nop 2
	ds_write2_b32 v134, v72, v73 offset0:48 offset1:116
	s_nop 1
	ds_write2_b32 v135, v68, v69 offset0:64 offset1:132
	ds_write2_b32 v136, v76, v77 offset0:80 offset1:148
	ds_write2_b32 v134, v74, v75 offset0:184 offset1:252
	ds_write2_b32 v140, v70, v71 offset0:72 offset1:140
	ds_write2_b32 v139, v78, v79 offset0:88 offset1:156

; #define LAS __attribute__((address_space(3)))
; __device__ __forceinline__ unsigned f2bf(float f) { return pk2(f, f) & 0xFFFFu; }
; __device__ __forceinline__ f32x4 mfma16(bf16x8 a, bf16x8 b, f32x4 c) { return __builtin_amdgcn_mfma_f32_16x16x32_bf16(a, b, c, 0, 0, 0); }
; __device__ __forceinline__ void ml_block(KP p, int e, int b, int hd, int half, LAS unsigned char* lds, const bf16_t* P, bf16_t* YB) {
;     ...
;             const int it = 2 * half + (wid & 1), jt = wid >> 1;
;             f32x4 acc = {0.f, 0.f, 0.f, 0.f};
; #pragma unroll
;             for (int kb = 0; kb < 4; ++kb) {
;                 const bf16x8 af = *(const LAS bf16x8*)(Qs + (it * 16 + fr) * 136 + kb * 32 + fq * 8);
;                 const bf16x8 bf = *(const LAS bf16x8*)(Ks + (jt * 16 + fr) * 136 + kb * 32 + fq * 8);
;                 acc = mfma16(af, bf, acc);
;             }
;             const int j = jt * 16 + fr; const float cj = Ip[j] - Bc[j];
; #pragma unroll
;             for (int jj = 0; jj < 4; ++jj) {
;                 const int i = it * 16 + fq * 4 + jj;
;                 const float v = (j <= i) ? acc[jj] * __expf(Bc[i] + cj) : 0.f;
;                 Ss[i * 72 + j] = (bf16_t)f2bf(v);
;             }
.LBB0_351:
	s_waitcnt lgkmcnt(0)
	s_barrier
	ds_read_b128 v[212:215], v140
	ds_read_b128 v[46:49], v142 offset:17408
	ds_read_b128 v[216:219], v140 offset:64
	ds_read_b128 v[50:53], v142 offset:17472
	ds_read_b128 v[220:223], v140 offset:128
	ds_read_b128 v[228:231], v142 offset:17536
	v_lshl_add_u32 v226, v143, 2, s56
	v_lshlrev_b32_e32 v234, 2, v141
	ds_read_b64 v[224:225], v226
	ds_read_b64 v[232:233], v226 offset:8
	v_add_u32_e32 v226, s69, v234
	v_add_u32_e32 v234, s56, v234
	ds_read_b32 v226, v226
	ds_read_b32 v234, v234
	s_waitcnt lgkmcnt(8)
	v_mfma_f32_16x16x32_bf16 v[42:45], v[212:215], v[46:49], 0
	ds_read_b128 v[212:215], v140 offset:192
	ds_read_b128 v[46:49], v142 offset:17600
	s_waitcnt lgkmcnt(8)
	v_mfma_f32_16x16x32_bf16 v[42:45], v[216:219], v[50:53], v[42:45]
	s_waitcnt lgkmcnt(6)
	v_mfma_f32_16x16x32_bf16 v[42:45], v[220:223], v[228:231], v[42:45]
	s_waitcnt lgkmcnt(0)
	v_mfma_f32_16x16x32_bf16 v[42:45], v[212:215], v[46:49], v[42:45]
	s_nop 3
	v_mov_b32_e32 v48, 0
	v_mov_b32_e32 v49, 0
	v_sub_f32_e32 v46, v226, v234
	s_and_saveexec_b64 s[46:47], s[26:27]
	s_cbranch_execz .LBB0_353
	v_add_f32_e32 v49, v46, v224
	v_mul_f32_e32 v49, 0x3fb8aa3b, v49
	v_exp_f32_e32 v49, v49
	s_nop 0
	v_mul_f32_e32 v42, v42, v49
	v_cvt_pk_bf16_f32 v49, v42, s0
.LBB0_353:
	s_or_b64 exec, exec, s[46:47]
	ds_write_b16 v176, v49 offset:34816
	s_and_saveexec_b64 s[46:47], s[28:29]
	s_cbranch_execz .LBB0_355
	v_add_f32_e32 v42, v46, v225
	v_mul_f32_e32 v42, 0x3fb8aa3b, v42
	v_exp_f32_e32 v42, v42
	s_nop 0
	v_mul_f32_e32 v42, v43, v42
	v_cvt_pk_bf16_f32 v48, v42, s0
.LBB0_355:
	s_or_b64 exec, exec, s[46:47]
	v_mov_b32_e32 v42, 0
	v_mov_b32_e32 v43, 0
	ds_write_b16 v176, v48 offset:34960
	s_and_saveexec_b64 s[46:47], s[30:31]
	s_cbranch_execz .LBB0_357
	v_add_f32_e32 v43, v46, v232
	v_mul_f32_e32 v43, 0x3fb8aa3b, v43
	v_exp_f32_e32 v43, v43
	s_nop 0
	v_mul_f32_e32 v43, v44, v43
	v_cvt_pk_bf16_f32 v43, v43, s0
.LBB0_357:
	s_or_b64 exec, exec, s[46:47]
	ds_write_b16 v176, v43 offset:35104
	s_and_saveexec_b64 s[46:47], s[34:35]
	s_cbranch_execz .LBB0_359
	v_add_f32_e32 v42, v46, v233
	v_mul_f32_e32 v42, 0x3fb8aa3b, v42
	v_exp_f32_e32 v42, v42
	s_nop 0
	v_mul_f32_e32 v42, v45, v42
	v_cvt_pk_bf16_f32 v42, v42, s0

; #define LAS __attribute__((address_space(3)))
; __device__ __forceinline__ f32x4 mfma16(bf16x8 a, bf16x8 b, f32x4 c) { return __builtin_amdgcn_mfma_f32_16x16x32_bf16(a, b, c, 0, 0, 0); }
; __device__ __forceinline__ void ml_block(KP p, int e, int b, int hd, int half, LAS unsigned char* lds, const bf16_t* P, bf16_t* YB) {
;     ...
;         const int oit = 2 * half + (wid & 1), oq = wid >> 1, oet0 = oq == 0 ? 0 : 1 + 2 * oq, onet = oq == 0 ? 3 : 2;
;         {
; #pragma unroll
;             for (int q = 0; q < 3; ++q) {
;                 ot[q] = (f32x4){0.f, 0.f, 0.f, 0.f};
;                 if (q < onet) {
;                     const int et = oet0 + q;
;                     f32x4 a1 = {0.f, 0.f, 0.f, 0.f}, a2 = {0.f, 0.f, 0.f, 0.f};
; #pragma unroll
;                     for (int kb = 0; kb < 2; ++kb) {
;                         const bf16x8 af = *(const LAS bf16x8*)(Ss + (oit * 16 + fr) * 72 + kb * 32 + fq * 8);
;                         const bf16x8 bf = *(const LAS bf16x8*)(VT + (et * 16 + fr) * 72 + kb * 32 + fq * 8);
;                         a1 = mfma16(af, bf, a1);
;                     }
; #pragma unroll
;                     for (int kb = 0; kb < 4; ++kb) {
;                         const bf16x8 af = *(const LAS bf16x8*)(Qs + (oit * 16 + fr) * 136 + kb * 32 + fq * 8);
;                         const bf16x8 bf = *(const LAS bf16x8*)(CT + (et * 16 + fr) * 136 + kb * 32 + fq * 8);
;                         a2 = mfma16(af, bf, a2);
;                     }
; #pragma unroll
;                     for (int jj = 0; jj < 4; ++jj) ot[q][jj] = a1[jj] + __expf(Bc[oit * 16 + fq * 4 + jj]) * a2[jj];
;                 }
.LBB0_362:
	s_or_b64 exec, exec, s[46:47]
	s_waitcnt lgkmcnt(0)
	s_barrier
	ds_read_b128 v[74:77], v140
	v_add_u32_e32 v66, v145, v164
	ds_read_b128 v[42:45], v66
	ds_read_b128 v[58:61], v140 offset:64
	ds_read_b128 v[46:49], v66 offset:64
	ds_read_b128 v[62:65], v140 offset:128
	ds_read_b128 v[50:53], v66 offset:128
	v_add_u32_e32 v78, v88, v163
	s_waitcnt lgkmcnt(4)
	v_mfma_f32_16x16x32_bf16 v[42:45], v[74:77], v[42:45], 0
	s_waitcnt lgkmcnt(2)
	v_mfma_f32_16x16x32_bf16 v[42:45], v[58:61], v[46:49], v[42:45]
	ds_read_b128 v[54:57], v144 offset:34816
	ds_read_b128 v[70:73], v140 offset:192
	ds_read_b128 v[46:49], v66 offset:192
	s_waitcnt lgkmcnt(3)
	v_mfma_f32_16x16x32_bf16 v[42:45], v[62:65], v[50:53], v[42:45]
	ds_read_b128 v[50:53], v78 offset:62464
	ds_read_b128 v[66:69], v144 offset:34880
	ds_read_b128 v[78:81], v78 offset:62528
	ds_read_b128 v[178:181], v169 offset:128
	s_waitcnt lgkmcnt(3)
	v_mfma_f32_16x16x32_bf16 v[104:107], v[54:57], v[50:53], 0
	v_mfma_f32_16x16x32_bf16 v[50:53], v[70:73], v[46:49], v[42:45]
	ds_read_b128 v[46:49], v169
	s_waitcnt lgkmcnt(2)
	v_mfma_f32_16x16x32_bf16 v[42:45], v[66:69], v[78:81], v[104:107]
	ds_read_b128 v[78:81], v169 offset:64
	s_waitcnt lgkmcnt(1)
	v_mfma_f32_16x16x32_bf16 v[46:49], v[74:77], v[46:49], 0
	s_nop 0
	v_add3_u32 v104, s56, v146, v147
	ds_read_b128 v[104:107], v104
	s_waitcnt lgkmcnt(0)
	v_mul_f32_e32 v104, 0x3fb8aa3b, v104
	v_mfma_f32_16x16x32_bf16 v[46:49], v[58:61], v[78:81], v[46:49]
	ds_read_b128 v[78:81], v169 offset:192
	v_exp_f32_e32 v108, v104
	v_mul_f32_e32 v104, 0x3fb8aa3b, v105
	v_mfma_f32_16x16x32_bf16 v[46:49], v[62:65], v[178:181], v[46:49]
	ds_read_b128 v[178:181], v168 offset:62464
	v_exp_f32_e32 v109, v104
	v_mul_f32_e32 v104, 0x3fb8aa3b, v106
	s_waitcnt lgkmcnt(1)
	v_mfma_f32_16x16x32_bf16 v[78:81], v[70:73], v[78:81], v[46:49]
	v_exp_f32_e32 v110, v104
	v_mul_f32_e32 v104, 0x3fb8aa3b, v107
	v_exp_f32_e32 v111, v104
	ds_read_b128 v[46:49], v168 offset:62528
	s_waitcnt lgkmcnt(1)
	v_mfma_f32_16x16x32_bf16 v[178:181], v[54:57], v[178:181], 0
	v_mov_b32_e32 v106, 0
	v_mov_b32_e32 v107, 0
	v_mov_b32_e32 v104, 0
	s_waitcnt lgkmcnt(0)
	v_mfma_f32_16x16x32_bf16 v[46:49], v[66:69], v[46:49], v[178:181]
	v_mov_b32_e32 v105, 0
	s_and_saveexec_b64 s[44:45], s[24:25]
	s_cbranch_execz .LBB0_364
	v_add_u32_e32 v178, v145, v165
	ds_read_b128 v[212:215], v178
	ds_read_b128 v[216:219], v178 offset:64
	ds_read_b128 v[220:223], v178 offset:128
	ds_read_b128 v[228:231], v178 offset:192
	ds_read_b128 v[104:107], v177 offset:62464
	ds_read_b128 v[178:181], v177 offset:62528
	s_waitcnt lgkmcnt(5)
	v_mfma_f32_16x16x32_bf16 v[74:77], v[74:77], v[212:215], 0
	s_waitcnt lgkmcnt(4)
	v_mfma_f32_16x16x32_bf16 v[58:61], v[58:61], v[216:219], v[74:77]
	s_waitcnt lgkmcnt(3)
	v_mfma_f32_16x16x32_bf16 v[58:61], v[62:65], v[220:223], v[58:61]
	s_waitcnt lgkmcnt(2)
	v_mfma_f32_16x16x32_bf16 v[58:61], v[70:73], v[228:231], v[58:61]
	s_waitcnt lgkmcnt(1)
	v_mfma_f32_16x16x32_bf16 v[54:57], v[54:57], v[104:107], 0
	s_waitcnt lgkmcnt(0)
	v_mfma_f32_16x16x32_bf16 v[54:57], v[66:69], v[178:181], v[54:57]
	s_nop 7
	v_pk_fma_f32 v[104:105], v[110:111], v[60:61], v[56:57]
	v_pk_fma_f32 v[106:107], v[108:109], v[58:59], v[54:55]

; #define LAS __attribute__((address_space(3)))
; __device__ __forceinline__ unsigned pk2(float lo, float hi) { const f32x2 v = {lo, hi}; const bf16x2n b = __builtin_convertvector(v, bf16x2n); return __builtin_bit_cast(unsigned, b); }
; __device__ __forceinline__ float rcp_(float x) { return __builtin_amdgcn_rcpf(x); }
; __device__ __forceinline__ void ml_block(KP p, int e, int b, int hd, int half, LAS unsigned char* lds, const bf16_t* P, bf16_t* YB) {
;     ...
;         {
;             const int i = half * 32 + wid * 4 + er; const size_t row = rbase + tb + i;
;             const float dn = rcp_(fmaxf(fabsf(Of[i * 148 + 128]), 1.0f));
;             const f32x4 ha = *(const LAS f32x4*)(Of + i * 148 + 8 * ecg) * dn, hb = *(const LAS f32x4*)(Of + i * 148 + 8 * ecg + 4) * dn;
;             float sm = ((ha.x + ha.y) + (ha.z + ha.w)) + ((hb.x + hb.y) + (hb.z + hb.w));
;             sm += dpp_f<0xB1>(sm); sm += dpp_f<0x4E>(sm); sm += dpp_f<0x141>(sm); sm += dpp_f<0x140>(sm);
;             const float mean = sm * (1.f / 128.f);
;             const f32x4 da = ha - mean, db = hb - mean;
;             float sv = ((da.x * da.x + da.y * da.y) + (da.z * da.z + da.w * da.w)) + ((db.x * db.x + db.y * db.y) + (db.z * db.z + db.w * db.w));
;             sv += dpp_f<0xB1>(sv); sv += dpp_f<0x4E>(sv); sv += dpp_f<0x141>(sv); sv += dpp_f<0x140>(sv);
;             const float rstd = __builtin_amdgcn_rsqf(sv * (1.f / 128.f) + 1e-6f);
;             const f32x4 na = *(const LAS f32x4*)(NG + 8 * ecg), nb2 = *(const LAS f32x4*)(NG + 8 * ecg + 4);
;             float y[8];
; #pragma unroll
;             for (int k = 0; k < 4; ++k) {
;                 const unsigned wv = (k == 0) ? og_r.x : (k == 1) ? og_r.y : (k == 2) ? og_r.z : og_r.w;
;                 const float g0 = sigmoidf_(__uint_as_float(wv << 16)), g1 = sigmoidf_(__uint_as_float(wv & 0xFFFF0000u));
;                 const float d0 = (k < 2) ? da[2 * k] : db[2 * k - 4], d1 = (k < 2) ? da[2 * k + 1] : db[2 * k - 3];
;                 const float n0 = (k < 2) ? na[2 * k] : nb2[2 * k - 4], n1 = (k < 2) ? na[2 * k + 1] : nb2[2 * k - 3];
;                 y[2 * k] = d0 * rstd * n0 * g0; y[2 * k + 1] = d1 * rstd * n1 * g1;
;             }
;             u32x4 w; w.x = pk2(y[0], y[1]); w.y = pk2(y[2], y[3]); w.z = pk2(y[4], y[5]); w.w = pk2(y[6], y[7]);
;             *(u32x4*)(YB + row * DM + 512 + hd * 128 + 8 * ecg) = w;
;         }
.LBB0_366:
	s_or_b64 exec, exec, s[44:45]
	s_waitcnt lgkmcnt(0)
	s_barrier
	ds_read_b32 v42, v149 offset:512
	v_add_u32_e32 v46, v149, v150
	s_andn2_b64 vcc, exec, s[42:43]
	ds_read_b128 v[212:215], v46
	ds_read_b128 v[216:219], v46 offset:16
	v_add_u32_e32 v226, 0x1f400, v150
	ds_read_b128 v[220:223], v226
	ds_read_b128 v[228:231], v226 offset:16
	s_waitcnt lgkmcnt(4)
	v_max_f32_e64 v42, |v42|, |v42|
	v_max_f32_e32 v42, 1.0, v42
	v_rcp_f32_e32 v56, v42
	s_waitcnt lgkmcnt(3)
	v_pk_mul_f32 v[52:53], v[212:213], v[56:57] op_sel_hi:[1,0]
	s_waitcnt lgkmcnt(2)
	v_pk_mul_f32 v[58:59], v[216:217], v[56:57] op_sel_hi:[1,0]
	v_pk_mul_f32 v[46:47], v[214:215], v[56:57] op_sel_hi:[1,0]
	v_pk_mul_f32 v[54:55], v[218:219], v[56:57] op_sel_hi:[1,0]
	v_mov_b32_e32 v60, v52
	v_mov_b32_e32 v61, v58
	v_mov_b32_e32 v58, v53
	v_pk_add_f32 v[52:53], v[60:61], v[58:59]
	v_mov_b32_e32 v58, v46
	v_mov_b32_e32 v59, v54
	v_mov_b32_e32 v54, v47
	v_pk_add_f32 v[46:47], v[58:59], v[54:55]
	s_nop 0
	v_pk_add_f32 v[46:47], v[52:53], v[46:47]
	s_nop 0
	v_add_f32_e32 v46, v46, v47
	s_nop 1
	v_add_f32_dpp v46, v46, v46 quad_perm:[1,0,3,2] row_mask:0xf bank_mask:0xf bound_ctrl:1
	s_nop 1
	v_add_f32_dpp v46, v46, v46 quad_perm:[2,3,0,1] row_mask:0xf bank_mask:0xf bound_ctrl:1
	s_nop 1
	v_add_f32_dpp v46, v46, v46 row_half_mirror row_mask:0xf bank_mask:0xf bound_ctrl:1
	s_nop 1
	v_add_f32_dpp v46, v46, v46 row_mirror row_mask:0xf bank_mask:0xf bound_ctrl:1
	v_mul_f32_e32 v58, 0xbc000000, v46
	v_pk_fma_f32 v[54:55], v[212:213], v[56:57], v[58:59] op_sel_hi:[1,0,0]
	v_pk_fma_f32 v[46:47], v[218:219], v[56:57], v[58:59] op_sel_hi:[1,0,0]
	v_pk_fma_f32 v[50:51], v[216:217], v[56:57], v[58:59] op_sel_hi:[1,0,0]
	v_pk_fma_f32 v[52:53], v[214:215], v[56:57], v[58:59] op_sel_hi:[1,0,0]
	v_mov_b32_e32 v44, v55
	v_mov_b32_e32 v45, v51
	v_mov_b32_e32 v42, v54
	v_mov_b32_e32 v43, v50
	v_pk_mul_f32 v[44:45], v[44:45], v[44:45]
	v_mov_b32_e32 v48, v53
	v_mov_b32_e32 v49, v47
	v_pk_fma_f32 v[42:43], v[42:43], v[42:43], v[44:45]
	v_mov_b32_e32 v44, v52
	v_mov_b32_e32 v45, v46
	v_pk_mul_f32 v[48:49], v[48:49], v[48:49]
	s_nop 0
	v_pk_fma_f32 v[44:45], v[44:45], v[44:45], v[48:49]
	v_lshlrev_b32_e32 v49, 16, v2
	v_mul_f32_e32 v49, 0xbfb8aa3b, v49
	v_exp_f32_e32 v49, v49
	v_pk_add_f32 v[42:43], v[42:43], v[44:45]
	v_add_f32_e32 v49, 1.0, v49
	v_add_f32_e32 v42, v42, v43
	v_rcp_f32_e32 v60, v49
	v_and_b32_e32 v49, 0xffff0000, v2
	v_add_f32_dpp v42, v42, v42 quad_perm:[1,0,3,2] row_mask:0xf bank_mask:0xf bound_ctrl:1
	v_mul_f32_e32 v49, 0xbfb8aa3b, v49
	v_exp_f32_e32 v49, v49
	v_add_f32_dpp v42, v42, v42 quad_perm:[2,3,0,1] row_mask:0xf bank_mask:0xf bound_ctrl:1
	v_add_f32_e32 v49, 1.0, v49
	s_nop 0
	v_add_f32_dpp v42, v42, v42 row_half_mirror row_mask:0xf bank_mask:0xf bound_ctrl:1
	v_rcp_f32_e32 v61, v49
	s_nop 0
	v_add_f32_dpp v42, v42, v42 row_mirror row_mask:0xf bank_mask:0xf bound_ctrl:1
	v_fmamk_f32 v42, v42, 0x3c000000, v238
	v_rsq_f32_e32 v48, v42
	s_waitcnt lgkmcnt(0)
	v_pk_mul_f32 v[54:55], v[54:55], v[48:49] op_sel_hi:[1,0]
	v_lshlrev_b32_e32 v49, 16, v3
	v_mul_f32_e32 v49, 0xbfb8aa3b, v49
	v_exp_f32_e32 v49, v49
	v_pk_mul_f32 v[54:55], v[220:221], v[54:55]
	v_add_f32_e32 v49, 1.0, v49
	v_rcp_f32_e32 v56, v49
	v_and_b32_e32 v49, 0xffff0000, v3
	v_mul_f32_e32 v49, 0xbfb8aa3b, v49
	v_exp_f32_e32 v49, v49
	v_pk_mul_f32 v[54:55], v[60:61], v[54:55]
	v_add_f32_e32 v49, 1.0, v49
	v_rcp_f32_e32 v57, v49
	v_pk_mul_f32 v[52:53], v[52:53], v[48:49] op_sel_hi:[1,0]
	v_lshlrev_b32_e32 v49, 16, v4
	v_mul_f32_e32 v49, 0xbfb8aa3b, v49
	v_exp_f32_e32 v49, v49
	v_pk_mul_f32 v[52:53], v[222:223], v[52:53]
	v_add_f32_e32 v49, 1.0, v49
	v_pk_mul_f32 v[52:53], v[56:57], v[52:53]
	v_rcp_f32_e32 v56, v49
	v_and_b32_e32 v49, 0xffff0000, v4
	v_mul_f32_e32 v49, 0xbfb8aa3b, v49
	v_exp_f32_e32 v49, v49
	s_nop 0
	v_add_f32_e32 v49, 1.0, v49
	v_rcp_f32_e32 v57, v49
	v_pk_mul_f32 v[50:51], v[50:51], v[48:49] op_sel_hi:[1,0]
	v_pk_mul_f32 v[46:47], v[46:47], v[48:49] op_sel_hi:[1,0]
	v_pk_mul_f32 v[42:43], v[228:229], v[50:51]
	v_pk_mul_f32 v[44:45], v[230:231], v[46:47]
	v_pk_mul_f32 v[50:51], v[56:57], v[42:43]
	v_lshlrev_b32_e32 v42, 16, v5
	v_and_b32_e32 v43, 0xffff0000, v5
	v_mul_f32_e32 v42, 0xbfb8aa3b, v42
	v_mul_f32_e32 v43, 0xbfb8aa3b, v43
	v_exp_f32_e32 v42, v42
	v_exp_f32_e32 v43, v43
	v_add_f32_e32 v42, 1.0, v42
	v_add_f32_e32 v43, 1.0, v43
	v_rcp_f32_e32 v42, v42
	v_rcp_f32_e32 v43, v43
	s_nop 0
	v_pk_mul_f32 v[46:47], v[42:43], v[44:45]
	v_cvt_pk_bf16_f32 v42, v54, v55
	v_cvt_pk_bf16_f32 v43, v52, v53
	v_cvt_pk_bf16_f32 v44, v50, v51
	v_cvt_pk_bf16_f32 v45, v46, v47
	v_lshl_add_u64 v[46:47], s[50:51], 0, v[100:101]
	global_store_dwordx4 v[46:47], v[42:45], off
	s_cbranch_vccnz .LBB0_326
	s_add_i32 s56, s41, s52
	v_lshl_add_u64 v[2:3], v[86:87], 0, s[56:57]
	v_mov_b64_e32 v[4:5], s[94:95]
	v_mad_u64_u32 v[4:5], s[42:43], v2, s81, v[4:5]
	v_mad_i32_i24 v5, v3, s81, v5
	v_lshl_add_u64 v[2:3], v[82:83], 1, v[4:5]
	v_lshl_add_u64 v[2:3], v[2:3], 0, v[0:1]
	v_add_co_u32_e32 v2, vcc, 0x1000, v2
	s_nop 1
	v_addc_co_u32_e32 v3, vcc, 0, v3, vcc
	global_load_dwordx4 v[2:5], v[2:3], off offset:1024
	s_branch .LBB0_326
